# diff attention with cross-pass prefetch, loop body moved by 4 bytes (placement check)
# speedup vs baseline: 1.0031x; 1.0031x over previous
; #define WAIT_BAR(N) asm volatile("s_waitcnt vmcnt(" #N ") lgkmcnt(0)\n\ts_barrier":::"memory")
;   #define DMA_K(t,slot) glds16(ksrc+(long)(t)*KVBLK*KP,(unsigned)__builtin_amdgcn_readfirstlane(kdst+(slot)))
;   #define DMA_V(t,slot) glds16(vsrc+(long)(t)*KVBLK*VP,(unsigned)__builtin_amdgcn_readfirstlane(vdst+(slot)))
;   #define XMASK(P0,P1,t) do{ if constexpr(MASKED){ bmask(P0,P1,mimg[(2*(t))*32],mimg[(2*(t)+1)*32],hi); } else { CMASK(P0,P1,t); } }while(0)
;   #define ROT() do{sl_prev=sl_cur;sl_cur=sl_next;sl_next=(sl_next==(NSLOT-1)*SLOTB)?0:sl_next+SLOTB;}while(0)
;     ...
;   DMA_K(2,2*SLOTB);
;   WAIT_BAR(3);
;   qkt(pA0,pA1,Kbase,qr,negm,r32,hi);asm volatile("s_nop 15\n\ts_nop 7":"+v"(pA0),"+v"(pA1));XMASK(pA0,pA1,0);
;   START(pA0,pA1);
;   _Pragma("unroll") for(int r=0;r<16;++r)pA1[r]=__builtin_amdgcn_exp2f(pA1[r]);
;   WAIT_BAR(0);
;   DMA_K(3,0);DMA_V(1,SLOTB);
;   ROT();
;   kload8(kf,kp0+sl_cur);
;   WAIT_BAR(2);
.Lfd_w2:
	s_barrier
	s_nop 0

; __device__ __forceinline__ unsigned cvtpk_s(float lo,float hi){f32x2_t v={lo,hi};bf16x2_t b=__builtin_convertvector(v,bf16x2_t);return __builtin_bit_cast(unsigned,b);}
;     ...
;     if(emode>=2){
;       #pragma unroll
;       for(int r=0;r<16;++r){
;         #pragma unroll
;         for(int d0=0;d0<2;++d0){ const float old=__uint_as_float((unsigned)stl[cr0(r)*64+d0*32]<<16); stl[cr0(r)*64+d0*32]=(bf16)(cvtpk_s(old-lam*(o[d0][r]*rli[r]),0.f)&0xffffu);} }
;     } else {
.Lfd_epi1:
	v_mov_b32_e32 v253, v252
	global_load_dwordx4 v[176:179], v253, s[86:87]
	v_add_u32_e32 v253, 0x2000, v253
	global_load_dwordx4 v[180:183], v253, s[86:87]
	v_add_u32_e32 v253, 0x2000, v253
	global_load_dwordx4 v[184:187], v253, s[86:87]
	v_add_u32_e32 v253, 0x2000, v253
	global_load_dwordx4 v[188:191], v253, s[86:87]
	v_add_u32_e32 v253, 0x2000, v253
	global_load_dwordx4 v[192:195], v253, s[86:87]
	v_add_u32_e32 v253, 0x2000, v253
	global_load_dwordx4 v[196:199], v253, s[86:87]
	v_add_u32_e32 v253, 0x2000, v253
	global_load_dwordx4 v[200:203], v253, s[86:87]
	v_add_u32_e32 v253, 0x2000, v253
	global_load_dwordx4 v[204:207], v253, s[86:87]
	s_waitcnt vmcnt(0)
	ds_write_b128 v219, v[176:179] offset:0
	ds_write_b128 v219, v[180:183] offset:1024
	ds_write_b128 v219, v[184:187] offset:2048
	ds_write_b128 v219, v[188:191] offset:3072
	ds_write_b128 v219, v[192:195] offset:4096
	ds_write_b128 v219, v[196:199] offset:5120
	ds_write_b128 v219, v[200:203] offset:6144
	ds_write_b128 v219, v[204:207] offset:7168
	s_waitcnt lgkmcnt(0)
	ds_read_u16 v128, v46 offset:0
	ds_read_u16 v129, v46 offset:256
	ds_read_u16 v130, v46 offset:512
	ds_read_u16 v131, v46 offset:768
	ds_read_u16 v132, v46 offset:2048
	ds_read_u16 v133, v46 offset:2304
	ds_read_u16 v134, v46 offset:2560
	ds_read_u16 v135, v46 offset:2816
	ds_read_u16 v136, v46 offset:4096
	ds_read_u16 v137, v46 offset:4352
	ds_read_u16 v138, v46 offset:4608
	ds_read_u16 v139, v46 offset:4864
	ds_read_u16 v140, v46 offset:6144
	ds_read_u16 v141, v46 offset:6400
	ds_read_u16 v142, v46 offset:6656
	ds_read_u16 v143, v46 offset:6912
	s_waitcnt lgkmcnt(0)
	v_mul_f32_e32 v4, v48, v112
	v_lshlrev_b32_e32 v5, 16, v128
	v_fma_f32 v4, -v216, v4, v5
	v_cvt_pk_bf16_f32 v4, v4, v4
	ds_write_b16 v46, v4 offset:0
	v_mul_f32_e32 v4, v49, v113
	v_lshlrev_b32_e32 v5, 16, v129
	v_fma_f32 v4, -v216, v4, v5
	v_cvt_pk_bf16_f32 v4, v4, v4
	ds_write_b16 v46, v4 offset:256
	v_mul_f32_e32 v4, v50, v114
	v_lshlrev_b32_e32 v5, 16, v130
	v_fma_f32 v4, -v216, v4, v5
	v_cvt_pk_bf16_f32 v4, v4, v4
	ds_write_b16 v46, v4 offset:512
	v_mul_f32_e32 v4, v51, v115
	v_lshlrev_b32_e32 v5, 16, v131
	v_fma_f32 v4, -v216, v4, v5
	v_cvt_pk_bf16_f32 v4, v4, v4
	ds_write_b16 v46, v4 offset:768
	v_mul_f32_e32 v4, v52, v116
	v_lshlrev_b32_e32 v5, 16, v132
	v_fma_f32 v4, -v216, v4, v5
	v_cvt_pk_bf16_f32 v4, v4, v4
	ds_write_b16 v46, v4 offset:2048
	v_mul_f32_e32 v4, v53, v117
	v_lshlrev_b32_e32 v5, 16, v133
	v_fma_f32 v4, -v216, v4, v5
	v_cvt_pk_bf16_f32 v4, v4, v4
	ds_write_b16 v46, v4 offset:2304
	v_mul_f32_e32 v4, v54, v118
	v_lshlrev_b32_e32 v5, 16, v134
	v_fma_f32 v4, -v216, v4, v5
	v_cvt_pk_bf16_f32 v4, v4, v4
	ds_write_b16 v46, v4 offset:2560
	v_mul_f32_e32 v4, v55, v119
	v_lshlrev_b32_e32 v5, 16, v135
	v_fma_f32 v4, -v216, v4, v5
	v_cvt_pk_bf16_f32 v4, v4, v4
	ds_write_b16 v46, v4 offset:2816
	v_mul_f32_e32 v4, v56, v120
	v_lshlrev_b32_e32 v5, 16, v136
	v_fma_f32 v4, -v216, v4, v5
	v_cvt_pk_bf16_f32 v4, v4, v4
	ds_write_b16 v46, v4 offset:4096
	v_mul_f32_e32 v4, v57, v121
	v_lshlrev_b32_e32 v5, 16, v137
	v_fma_f32 v4, -v216, v4, v5
	v_cvt_pk_bf16_f32 v4, v4, v4
	ds_write_b16 v46, v4 offset:4352
	v_mul_f32_e32 v4, v58, v122
	v_lshlrev_b32_e32 v5, 16, v138
	v_fma_f32 v4, -v216, v4, v5
	v_cvt_pk_bf16_f32 v4, v4, v4
	ds_write_b16 v46, v4 offset:4608
	v_mul_f32_e32 v4, v59, v123
	v_lshlrev_b32_e32 v5, 16, v139
	v_fma_f32 v4, -v216, v4, v5
	v_cvt_pk_bf16_f32 v4, v4, v4
	ds_write_b16 v46, v4 offset:4864
	v_mul_f32_e32 v4, v60, v124
	v_lshlrev_b32_e32 v5, 16, v140
	v_fma_f32 v4, -v216, v4, v5
	v_cvt_pk_bf16_f32 v4, v4, v4
	ds_write_b16 v46, v4 offset:6144
	v_mul_f32_e32 v4, v61, v125
	v_lshlrev_b32_e32 v5, 16, v141
	v_fma_f32 v4, -v216, v4, v5
	v_cvt_pk_bf16_f32 v4, v4, v4
	ds_write_b16 v46, v4 offset:6400
	v_mul_f32_e32 v4, v62, v126
	v_lshlrev_b32_e32 v5, 16, v142
	v_fma_f32 v4, -v216, v4, v5
	v_cvt_pk_bf16_f32 v4, v4, v4
	ds_write_b16 v46, v4 offset:6656
	v_mul_f32_e32 v4, v63, v127
	v_lshlrev_b32_e32 v5, 16, v143
	v_fma_f32 v4, -v216, v4, v5
	v_cvt_pk_bf16_f32 v4, v4, v4
	ds_write_b16 v46, v4 offset:6912
	ds_read_u16 v128, v46 offset:64
	ds_read_u16 v129, v46 offset:320
	ds_read_u16 v130, v46 offset:576
	ds_read_u16 v131, v46 offset:832
	ds_read_u16 v132, v46 offset:2112
	ds_read_u16 v133, v46 offset:2368
	ds_read_u16 v134, v46 offset:2624
	ds_read_u16 v135, v46 offset:2880
	ds_read_u16 v136, v46 offset:4160
	ds_read_u16 v137, v46 offset:4416
	ds_read_u16 v138, v46 offset:4672
	ds_read_u16 v139, v46 offset:4928
	ds_read_u16 v140, v46 offset:6208
	ds_read_u16 v141, v46 offset:6464
	ds_read_u16 v142, v46 offset:6720
	ds_read_u16 v143, v46 offset:6976
	s_waitcnt lgkmcnt(0)
; __device__ __forceinline__ unsigned cvtpk_s(float lo,float hi){f32x2_t v={lo,hi};bf16x2_t b=__builtin_convertvector(v,bf16x2_t);return __builtin_bit_cast(unsigned,b);}
;     ...
;     if(emode>=2){
;       #pragma unroll
;       for(int r=0;r<16;++r){
;         #pragma unroll
;         for(int d0=0;d0<2;++d0){ const float old=__uint_as_float((unsigned)stl[cr0(r)*64+d0*32]<<16); stl[cr0(r)*64+d0*32]=(bf16)(cvtpk_s(old-lam*(o[d0][r]*rli[r]),0.f)&0xffffu);} }
;     } else {
	v_mul_f32_e32 v4, v64, v112
	v_lshlrev_b32_e32 v5, 16, v128
	v_fma_f32 v4, -v216, v4, v5
	v_cvt_pk_bf16_f32 v4, v4, v4
	ds_write_b16 v46, v4 offset:64
	v_mul_f32_e32 v4, v65, v113
	v_lshlrev_b32_e32 v5, 16, v129
	v_fma_f32 v4, -v216, v4, v5
	v_cvt_pk_bf16_f32 v4, v4, v4
	ds_write_b16 v46, v4 offset:320
	v_mul_f32_e32 v4, v66, v114
	v_lshlrev_b32_e32 v5, 16, v130
	v_fma_f32 v4, -v216, v4, v5
	v_cvt_pk_bf16_f32 v4, v4, v4
	ds_write_b16 v46, v4 offset:576
	v_mul_f32_e32 v4, v67, v115
	v_lshlrev_b32_e32 v5, 16, v131
	v_fma_f32 v4, -v216, v4, v5
	v_cvt_pk_bf16_f32 v4, v4, v4
	ds_write_b16 v46, v4 offset:832
	v_mul_f32_e32 v4, v68, v116
	v_lshlrev_b32_e32 v5, 16, v132
	v_fma_f32 v4, -v216, v4, v5
	v_cvt_pk_bf16_f32 v4, v4, v4
	ds_write_b16 v46, v4 offset:2112
	v_mul_f32_e32 v4, v69, v117
	v_lshlrev_b32_e32 v5, 16, v133
	v_fma_f32 v4, -v216, v4, v5
	v_cvt_pk_bf16_f32 v4, v4, v4
	ds_write_b16 v46, v4 offset:2368
	v_mul_f32_e32 v4, v70, v118
	v_lshlrev_b32_e32 v5, 16, v134
	v_fma_f32 v4, -v216, v4, v5
	v_cvt_pk_bf16_f32 v4, v4, v4
	ds_write_b16 v46, v4 offset:2624
	v_mul_f32_e32 v4, v71, v119
	v_lshlrev_b32_e32 v5, 16, v135
	v_fma_f32 v4, -v216, v4, v5
	v_cvt_pk_bf16_f32 v4, v4, v4
	ds_write_b16 v46, v4 offset:2880
	v_mul_f32_e32 v4, v72, v120
	v_lshlrev_b32_e32 v5, 16, v136
	v_fma_f32 v4, -v216, v4, v5
	v_cvt_pk_bf16_f32 v4, v4, v4
	ds_write_b16 v46, v4 offset:4160
	v_mul_f32_e32 v4, v73, v121
	v_lshlrev_b32_e32 v5, 16, v137
	v_fma_f32 v4, -v216, v4, v5
	v_cvt_pk_bf16_f32 v4, v4, v4
	ds_write_b16 v46, v4 offset:4416
	v_mul_f32_e32 v4, v74, v122
	v_lshlrev_b32_e32 v5, 16, v138
	v_fma_f32 v4, -v216, v4, v5
	v_cvt_pk_bf16_f32 v4, v4, v4
	ds_write_b16 v46, v4 offset:4672
	v_mul_f32_e32 v4, v75, v123
	v_lshlrev_b32_e32 v5, 16, v139
	v_fma_f32 v4, -v216, v4, v5
	v_cvt_pk_bf16_f32 v4, v4, v4
	ds_write_b16 v46, v4 offset:4928
	v_mul_f32_e32 v4, v76, v124
	v_lshlrev_b32_e32 v5, 16, v140
	v_fma_f32 v4, -v216, v4, v5
	v_cvt_pk_bf16_f32 v4, v4, v4
	ds_write_b16 v46, v4 offset:6208
	v_mul_f32_e32 v4, v77, v125
	v_lshlrev_b32_e32 v5, 16, v141
	v_fma_f32 v4, -v216, v4, v5
	v_cvt_pk_bf16_f32 v4, v4, v4
	ds_write_b16 v46, v4 offset:6464
	v_mul_f32_e32 v4, v78, v126
	v_lshlrev_b32_e32 v5, 16, v142
	v_fma_f32 v4, -v216, v4, v5
	v_cvt_pk_bf16_f32 v4, v4, v4
	ds_write_b16 v46, v4 offset:6720
	v_mul_f32_e32 v4, v79, v127
	v_lshlrev_b32_e32 v5, 16, v143
	v_fma_f32 v4, -v216, v4, v5
	v_cvt_pk_bf16_f32 v4, v4, v4
	ds_write_b16 v46, v4 offset:6976
	ds_read_u16 v128, v46 offset:128
	ds_read_u16 v129, v46 offset:384
	ds_read_u16 v130, v46 offset:640
	ds_read_u16 v131, v46 offset:896
	ds_read_u16 v132, v46 offset:2176
	ds_read_u16 v133, v46 offset:2432
	ds_read_u16 v134, v46 offset:2688
	ds_read_u16 v135, v46 offset:2944
	ds_read_u16 v136, v46 offset:4224
	ds_read_u16 v137, v46 offset:4480
	ds_read_u16 v138, v46 offset:4736
	ds_read_u16 v139, v46 offset:4992
	ds_read_u16 v140, v46 offset:6272
	ds_read_u16 v141, v46 offset:6528
	ds_read_u16 v142, v46 offset:6784
	ds_read_u16 v143, v46 offset:7040
	s_waitcnt lgkmcnt(0)
	v_mul_f32_e32 v4, v80, v112
	v_lshlrev_b32_e32 v5, 16, v128
	v_fma_f32 v4, -v216, v4, v5
	v_cvt_pk_bf16_f32 v4, v4, v4
	ds_write_b16 v46, v4 offset:128
	v_mul_f32_e32 v4, v81, v113
	v_lshlrev_b32_e32 v5, 16, v129
	v_fma_f32 v4, -v216, v4, v5
	v_cvt_pk_bf16_f32 v4, v4, v4
	ds_write_b16 v46, v4 offset:384
	v_mul_f32_e32 v4, v82, v114
	v_lshlrev_b32_e32 v5, 16, v130
	v_fma_f32 v4, -v216, v4, v5
	v_cvt_pk_bf16_f32 v4, v4, v4
	ds_write_b16 v46, v4 offset:640
	v_mul_f32_e32 v4, v83, v115
	v_lshlrev_b32_e32 v5, 16, v131
	v_fma_f32 v4, -v216, v4, v5
	v_cvt_pk_bf16_f32 v4, v4, v4
	ds_write_b16 v46, v4 offset:896
	v_mul_f32_e32 v4, v84, v116
	v_lshlrev_b32_e32 v5, 16, v132
	v_fma_f32 v4, -v216, v4, v5
	v_cvt_pk_bf16_f32 v4, v4, v4
	ds_write_b16 v46, v4 offset:2176
	v_mul_f32_e32 v4, v85, v117
	v_lshlrev_b32_e32 v5, 16, v133
	v_fma_f32 v4, -v216, v4, v5
	v_cvt_pk_bf16_f32 v4, v4, v4
	ds_write_b16 v46, v4 offset:2432
	v_mul_f32_e32 v4, v86, v118
	v_lshlrev_b32_e32 v5, 16, v134
	v_fma_f32 v4, -v216, v4, v5
	v_cvt_pk_bf16_f32 v4, v4, v4
	ds_write_b16 v46, v4 offset:2688
	v_mul_f32_e32 v4, v87, v119
	v_lshlrev_b32_e32 v5, 16, v135
	v_fma_f32 v4, -v216, v4, v5
	v_cvt_pk_bf16_f32 v4, v4, v4
	ds_write_b16 v46, v4 offset:2944
	v_mul_f32_e32 v4, v88, v120
	v_lshlrev_b32_e32 v5, 16, v136
	v_fma_f32 v4, -v216, v4, v5
	v_cvt_pk_bf16_f32 v4, v4, v4
	ds_write_b16 v46, v4 offset:4224
	v_mul_f32_e32 v4, v89, v121
	v_lshlrev_b32_e32 v5, 16, v137
	v_fma_f32 v4, -v216, v4, v5
	v_cvt_pk_bf16_f32 v4, v4, v4
	ds_write_b16 v46, v4 offset:4480
	v_mul_f32_e32 v4, v90, v122
	v_lshlrev_b32_e32 v5, 16, v138
	v_fma_f32 v4, -v216, v4, v5
	v_cvt_pk_bf16_f32 v4, v4, v4
	ds_write_b16 v46, v4 offset:4736
	v_mul_f32_e32 v4, v91, v123
	v_lshlrev_b32_e32 v5, 16, v139
	v_fma_f32 v4, -v216, v4, v5
	v_cvt_pk_bf16_f32 v4, v4, v4
	ds_write_b16 v46, v4 offset:4992
	v_mul_f32_e32 v4, v92, v124
	v_lshlrev_b32_e32 v5, 16, v140
	v_fma_f32 v4, -v216, v4, v5
	v_cvt_pk_bf16_f32 v4, v4, v4
	ds_write_b16 v46, v4 offset:6272
	v_mul_f32_e32 v4, v93, v125
	v_lshlrev_b32_e32 v5, 16, v141
	v_fma_f32 v4, -v216, v4, v5
	v_cvt_pk_bf16_f32 v4, v4, v4
	ds_write_b16 v46, v4 offset:6528
	v_mul_f32_e32 v4, v94, v126
	v_lshlrev_b32_e32 v5, 16, v142
	v_fma_f32 v4, -v216, v4, v5
	v_cvt_pk_bf16_f32 v4, v4, v4
	ds_write_b16 v46, v4 offset:6784
	v_mul_f32_e32 v4, v95, v127
	v_lshlrev_b32_e32 v5, 16, v143
	v_fma_f32 v4, -v216, v4, v5
	v_cvt_pk_bf16_f32 v4, v4, v4
	ds_write_b16 v46, v4 offset:7040
	ds_read_u16 v128, v46 offset:192
	ds_read_u16 v129, v46 offset:448
	ds_read_u16 v130, v46 offset:704
	ds_read_u16 v131, v46 offset:960
	ds_read_u16 v132, v46 offset:2240
	ds_read_u16 v133, v46 offset:2496
	ds_read_u16 v134, v46 offset:2752
	ds_read_u16 v135, v46 offset:3008
	ds_read_u16 v136, v46 offset:4288
	ds_read_u16 v137, v46 offset:4544
	ds_read_u16 v138, v46 offset:4800
	ds_read_u16 v139, v46 offset:5056
	ds_read_u16 v140, v46 offset:6336
	ds_read_u16 v141, v46 offset:6592
	ds_read_u16 v142, v46 offset:6848
	ds_read_u16 v143, v46 offset:7104
	s_waitcnt lgkmcnt(0)
; __device__ __forceinline__ unsigned cvtpk_s(float lo,float hi){f32x2_t v={lo,hi};bf16x2_t b=__builtin_convertvector(v,bf16x2_t);return __builtin_bit_cast(unsigned,b);}
; #define ATTN_STORE16(p,v) st16_wt((p),(v))
;     ...
;     if(emode>=2){
;       #pragma unroll
;       for(int r=0;r<16;++r){
;         #pragma unroll
;         for(int d0=0;d0<2;++d0){ const float old=__uint_as_float((unsigned)stl[cr0(r)*64+d0*32]<<16); stl[cr0(r)*64+d0*32]=(bf16)(cvtpk_s(old-lam*(o[d0][r]*rli[r]),0.f)&0xffffu);} }
;     } else {
;     ...
;     } else if(emode==3){
;       #pragma unroll
;       for(int i=0;i<4;++i){const int row=i*8+(lane>>3),ch=lane&7;
;         const u32x4 v0=*(const u32x4*)(stg+row*64+ch*8), v1=*(const u32x4*)(stg+2048+row*64+ch*8);
;         float f[16]; float ss=0.f;
;         #pragma unroll
;         for(int j=0;j<4;++j){ f[2*j]=__uint_as_float(v0[j]<<16); f[2*j+1]=__uint_as_float(v0[j]&0xffff0000u); f[8+2*j]=__uint_as_float(v1[j]<<16); f[8+2*j+1]=__uint_as_float(v1[j]&0xffff0000u); }
;         #pragma unroll
;         for(int j=0;j<16;++j)ss+=f[j]*f[j];
;         ss+=__shfl_xor(ss,1); ss+=__shfl_xor(ss,2); ss+=__shfl_xor(ss,4);
;         const float rn=__builtin_amdgcn_rsqf(ss*(1.f/128.f)+1e-6f)*0.8f;
;         u32x4 w0,w1;
;         #pragma unroll
;         for(int j=0;j<4;++j){ w0[j]=cvtpk_s(f[2*j]*rn,f[2*j+1]*rn); w1[j]=cvtpk_s(f[8+2*j]*rn,f[8+2*j+1]*rn); }
;         ATTN_STORE16(Ow+(long)row*OP+ch*8,w0); ATTN_STORE16(Ow+(long)row*OP+64+ch*8,w1);}
	v_mul_f32_e32 v4, v96, v112
	v_lshlrev_b32_e32 v5, 16, v128
	v_fma_f32 v4, -v216, v4, v5
	v_cvt_pk_bf16_f32 v4, v4, v4
	ds_write_b16 v46, v4 offset:192
	v_mul_f32_e32 v4, v97, v113
	v_lshlrev_b32_e32 v5, 16, v129
	v_fma_f32 v4, -v216, v4, v5
	v_cvt_pk_bf16_f32 v4, v4, v4
	ds_write_b16 v46, v4 offset:448
	v_mul_f32_e32 v4, v98, v114
	v_lshlrev_b32_e32 v5, 16, v130
	v_fma_f32 v4, -v216, v4, v5
	v_cvt_pk_bf16_f32 v4, v4, v4
	ds_write_b16 v46, v4 offset:704
	v_mul_f32_e32 v4, v99, v115
	v_lshlrev_b32_e32 v5, 16, v131
	v_fma_f32 v4, -v216, v4, v5
	v_cvt_pk_bf16_f32 v4, v4, v4
	ds_write_b16 v46, v4 offset:960
	v_mul_f32_e32 v4, v100, v116
	v_lshlrev_b32_e32 v5, 16, v132
	v_fma_f32 v4, -v216, v4, v5
	v_cvt_pk_bf16_f32 v4, v4, v4
	ds_write_b16 v46, v4 offset:2240
	v_mul_f32_e32 v4, v101, v117
	v_lshlrev_b32_e32 v5, 16, v133
	v_fma_f32 v4, -v216, v4, v5
	v_cvt_pk_bf16_f32 v4, v4, v4
	ds_write_b16 v46, v4 offset:2496
	v_mul_f32_e32 v4, v102, v118
	v_lshlrev_b32_e32 v5, 16, v134
	v_fma_f32 v4, -v216, v4, v5
	v_cvt_pk_bf16_f32 v4, v4, v4
	ds_write_b16 v46, v4 offset:2752
	v_mul_f32_e32 v4, v103, v119
	v_lshlrev_b32_e32 v5, 16, v135
	v_fma_f32 v4, -v216, v4, v5
	v_cvt_pk_bf16_f32 v4, v4, v4
	ds_write_b16 v46, v4 offset:3008
	v_mul_f32_e32 v4, v104, v120
	v_lshlrev_b32_e32 v5, 16, v136
	v_fma_f32 v4, -v216, v4, v5
	v_cvt_pk_bf16_f32 v4, v4, v4
	ds_write_b16 v46, v4 offset:4288
	v_mul_f32_e32 v4, v105, v121
	v_lshlrev_b32_e32 v5, 16, v137
	v_fma_f32 v4, -v216, v4, v5
	v_cvt_pk_bf16_f32 v4, v4, v4
	ds_write_b16 v46, v4 offset:4544
	v_mul_f32_e32 v4, v106, v122
	v_lshlrev_b32_e32 v5, 16, v138
	v_fma_f32 v4, -v216, v4, v5
	v_cvt_pk_bf16_f32 v4, v4, v4
	ds_write_b16 v46, v4 offset:4800
	v_mul_f32_e32 v4, v107, v123
	v_lshlrev_b32_e32 v5, 16, v139
	v_fma_f32 v4, -v216, v4, v5
	v_cvt_pk_bf16_f32 v4, v4, v4
	ds_write_b16 v46, v4 offset:5056
	v_mul_f32_e32 v4, v108, v124
	v_lshlrev_b32_e32 v5, 16, v140
	v_fma_f32 v4, -v216, v4, v5
	v_cvt_pk_bf16_f32 v4, v4, v4
	ds_write_b16 v46, v4 offset:6336
	v_mul_f32_e32 v4, v109, v125
	v_lshlrev_b32_e32 v5, 16, v141
	v_fma_f32 v4, -v216, v4, v5
	v_cvt_pk_bf16_f32 v4, v4, v4
	ds_write_b16 v46, v4 offset:6592
	v_mul_f32_e32 v4, v110, v126
	v_lshlrev_b32_e32 v5, 16, v142
	v_fma_f32 v4, -v216, v4, v5
	v_cvt_pk_bf16_f32 v4, v4, v4
	ds_write_b16 v46, v4 offset:6848
	v_mul_f32_e32 v4, v111, v127
	v_lshlrev_b32_e32 v5, 16, v143
	v_fma_f32 v4, -v216, v4, v5
	v_cvt_pk_bf16_f32 v4, v4, v4
	ds_write_b16 v46, v4 offset:7104
	s_waitcnt lgkmcnt(0)
	ds_read_b128 v[176:179], v219 offset:0
	ds_read_b128 v[180:183], v219 offset:1024
	ds_read_b128 v[184:187], v219 offset:2048
	ds_read_b128 v[188:191], v219 offset:3072
	ds_read_b128 v[192:195], v219 offset:4096
	ds_read_b128 v[196:199], v219 offset:5120
	ds_read_b128 v[200:203], v219 offset:6144
	ds_read_b128 v[204:207], v219 offset:7168
	s_waitcnt lgkmcnt(0)
	v_mov_b32_e32 v37, 0x3c000000
	v_mov_b32_e32 v38, 0x358637bd
	v_lshlrev_b32_e32 v112, 16, v176
	v_and_b32_e32 v113, 0xffff0000, v176
	v_lshlrev_b32_e32 v114, 16, v177
	v_and_b32_e32 v115, 0xffff0000, v177
	v_lshlrev_b32_e32 v116, 16, v178
	v_and_b32_e32 v117, 0xffff0000, v178
	v_lshlrev_b32_e32 v118, 16, v179
	v_and_b32_e32 v119, 0xffff0000, v179
	v_mul_f32_e32 v4, v112, v112
	v_fmac_f32_e32 v4, v113, v113
	v_fmac_f32_e32 v4, v114, v114
	v_fmac_f32_e32 v4, v115, v115
	v_fmac_f32_e32 v4, v116, v116
	v_fmac_f32_e32 v4, v117, v117
	v_fmac_f32_e32 v4, v118, v118
	v_fmac_f32_e32 v4, v119, v119
	s_nop 1
	v_mov_b32_dpp v5, v4 row_ror:8 row_mask:0xf bank_mask:0xf
	v_add_f32_e32 v4, v4, v5
	s_nop 1
	v_mov_b32_dpp v5, v4 row_ror:4 row_mask:0xf bank_mask:0xf
	v_add_f32_e32 v4, v4, v5
	s_nop 1
	v_mov_b32_dpp v5, v4 row_ror:2 row_mask:0xf bank_mask:0xf
	v_add_f32_e32 v4, v4, v5
	s_nop 1
	v_mov_b32_dpp v5, v4 row_ror:1 row_mask:0xf bank_mask:0xf
	v_add_f32_e32 v4, v4, v5
	v_fma_f32 v4, v4, v37, v38
	v_rsq_f32_e32 v4, v4
	s_nop 0
	v_mul_f32_e32 v4, 0x3f4ccccd, v4
	v_mul_f32_e32 v112, v112, v4
	v_mul_f32_e32 v113, v113, v4
	v_mul_f32_e32 v114, v114, v4
	v_mul_f32_e32 v115, v115, v4
	v_mul_f32_e32 v116, v116, v4
	v_mul_f32_e32 v117, v117, v4
	v_mul_f32_e32 v118, v118, v4
	v_mul_f32_e32 v119, v119, v4
	v_cvt_pk_bf16_f32 v176, v112, v113
	v_cvt_pk_bf16_f32 v177, v114, v115
	v_cvt_pk_bf16_f32 v178, v116, v117
	v_cvt_pk_bf16_f32 v179, v118, v119
	v_mov_b32_e32 v253, v252
	global_store_dwordx4 v253, v[176:179], s[86:87]
	v_lshlrev_b32_e32 v112, 16, v180
	v_and_b32_e32 v113, 0xffff0000, v180
	v_lshlrev_b32_e32 v114, 16, v181
	v_and_b32_e32 v115, 0xffff0000, v181
	v_lshlrev_b32_e32 v116, 16, v182
	v_and_b32_e32 v117, 0xffff0000, v182
	v_lshlrev_b32_e32 v118, 16, v183
	v_and_b32_e32 v119, 0xffff0000, v183
	v_mul_f32_e32 v4, v112, v112
	v_fmac_f32_e32 v4, v113, v113
	v_fmac_f32_e32 v4, v114, v114
	v_fmac_f32_e32 v4, v115, v115
	v_fmac_f32_e32 v4, v116, v116
	v_fmac_f32_e32 v4, v117, v117
	v_fmac_f32_e32 v4, v118, v118
	v_fmac_f32_e32 v4, v119, v119
	s_nop 1
	v_mov_b32_dpp v5, v4 row_ror:8 row_mask:0xf bank_mask:0xf
	v_add_f32_e32 v4, v4, v5
	s_nop 1
	v_mov_b32_dpp v5, v4 row_ror:4 row_mask:0xf bank_mask:0xf
	v_add_f32_e32 v4, v4, v5
	s_nop 1
	v_mov_b32_dpp v5, v4 row_ror:2 row_mask:0xf bank_mask:0xf
	v_add_f32_e32 v4, v4, v5
	s_nop 1
	v_mov_b32_dpp v5, v4 row_ror:1 row_mask:0xf bank_mask:0xf
	v_add_f32_e32 v4, v4, v5
	v_fma_f32 v4, v4, v37, v38
	v_rsq_f32_e32 v4, v4
	s_nop 0
	v_mul_f32_e32 v4, 0x3f4ccccd, v4
	v_mul_f32_e32 v112, v112, v4
	v_mul_f32_e32 v113, v113, v4
	v_mul_f32_e32 v114, v114, v4
	v_mul_f32_e32 v115, v115, v4
	v_mul_f32_e32 v116, v116, v4
	v_mul_f32_e32 v117, v117, v4
	v_mul_f32_e32 v118, v118, v4
	v_mul_f32_e32 v119, v119, v4
; __device__ __forceinline__ unsigned cvtpk_s(float lo,float hi){f32x2_t v={lo,hi};bf16x2_t b=__builtin_convertvector(v,bf16x2_t);return __builtin_bit_cast(unsigned,b);}
; #define ATTN_STORE16(p,v) st16_wt((p),(v))
;     ...
;     } else if(emode==3){
;       #pragma unroll
;       for(int i=0;i<4;++i){const int row=i*8+(lane>>3),ch=lane&7;
;         const u32x4 v0=*(const u32x4*)(stg+row*64+ch*8), v1=*(const u32x4*)(stg+2048+row*64+ch*8);
;         float f[16]; float ss=0.f;
;         #pragma unroll
;         for(int j=0;j<4;++j){ f[2*j]=__uint_as_float(v0[j]<<16); f[2*j+1]=__uint_as_float(v0[j]&0xffff0000u); f[8+2*j]=__uint_as_float(v1[j]<<16); f[8+2*j+1]=__uint_as_float(v1[j]&0xffff0000u); }
;         #pragma unroll
;         for(int j=0;j<16;++j)ss+=f[j]*f[j];
;         ss+=__shfl_xor(ss,1); ss+=__shfl_xor(ss,2); ss+=__shfl_xor(ss,4);
;         const float rn=__builtin_amdgcn_rsqf(ss*(1.f/128.f)+1e-6f)*0.8f;
;         u32x4 w0,w1;
;         #pragma unroll
;         for(int j=0;j<4;++j){ w0[j]=cvtpk_s(f[2*j]*rn,f[2*j+1]*rn); w1[j]=cvtpk_s(f[8+2*j]*rn,f[8+2*j+1]*rn); }
;         ATTN_STORE16(Ow+(long)row*OP+ch*8,w0); ATTN_STORE16(Ow+(long)row*OP+64+ch*8,w1);}
	v_cvt_pk_bf16_f32 v180, v112, v113
	v_cvt_pk_bf16_f32 v181, v114, v115
	v_cvt_pk_bf16_f32 v182, v116, v117
	v_cvt_pk_bf16_f32 v183, v118, v119
	v_add_u32_e32 v253, 0x2000, v253
	global_store_dwordx4 v253, v[180:183], s[86:87]
	v_lshlrev_b32_e32 v112, 16, v184
	v_and_b32_e32 v113, 0xffff0000, v184
	v_lshlrev_b32_e32 v114, 16, v185
	v_and_b32_e32 v115, 0xffff0000, v185
	v_lshlrev_b32_e32 v116, 16, v186
	v_and_b32_e32 v117, 0xffff0000, v186
	v_lshlrev_b32_e32 v118, 16, v187
	v_and_b32_e32 v119, 0xffff0000, v187
	v_mul_f32_e32 v4, v112, v112
	v_fmac_f32_e32 v4, v113, v113
	v_fmac_f32_e32 v4, v114, v114
	v_fmac_f32_e32 v4, v115, v115
	v_fmac_f32_e32 v4, v116, v116
	v_fmac_f32_e32 v4, v117, v117
	v_fmac_f32_e32 v4, v118, v118
	v_fmac_f32_e32 v4, v119, v119
	s_nop 1
	v_mov_b32_dpp v5, v4 row_ror:8 row_mask:0xf bank_mask:0xf
	v_add_f32_e32 v4, v4, v5
	s_nop 1
	v_mov_b32_dpp v5, v4 row_ror:4 row_mask:0xf bank_mask:0xf
	v_add_f32_e32 v4, v4, v5
	s_nop 1
	v_mov_b32_dpp v5, v4 row_ror:2 row_mask:0xf bank_mask:0xf
	v_add_f32_e32 v4, v4, v5
	s_nop 1
	v_mov_b32_dpp v5, v4 row_ror:1 row_mask:0xf bank_mask:0xf
	v_add_f32_e32 v4, v4, v5
	v_fma_f32 v4, v4, v37, v38
	v_rsq_f32_e32 v4, v4
	s_nop 0
	v_mul_f32_e32 v4, 0x3f4ccccd, v4
	v_mul_f32_e32 v112, v112, v4
	v_mul_f32_e32 v113, v113, v4
	v_mul_f32_e32 v114, v114, v4
	v_mul_f32_e32 v115, v115, v4
	v_mul_f32_e32 v116, v116, v4
	v_mul_f32_e32 v117, v117, v4
	v_mul_f32_e32 v118, v118, v4
	v_mul_f32_e32 v119, v119, v4
	v_cvt_pk_bf16_f32 v184, v112, v113
	v_cvt_pk_bf16_f32 v185, v114, v115
	v_cvt_pk_bf16_f32 v186, v116, v117
	v_cvt_pk_bf16_f32 v187, v118, v119
	v_add_u32_e32 v253, 0x2000, v253
	global_store_dwordx4 v253, v[184:187], s[86:87]
	v_lshlrev_b32_e32 v112, 16, v188
	v_and_b32_e32 v113, 0xffff0000, v188
	v_lshlrev_b32_e32 v114, 16, v189
	v_and_b32_e32 v115, 0xffff0000, v189
	v_lshlrev_b32_e32 v116, 16, v190
	v_and_b32_e32 v117, 0xffff0000, v190
	v_lshlrev_b32_e32 v118, 16, v191
	v_and_b32_e32 v119, 0xffff0000, v191
	v_mul_f32_e32 v4, v112, v112
	v_fmac_f32_e32 v4, v113, v113
	v_fmac_f32_e32 v4, v114, v114
	v_fmac_f32_e32 v4, v115, v115
	v_fmac_f32_e32 v4, v116, v116
	v_fmac_f32_e32 v4, v117, v117
	v_fmac_f32_e32 v4, v118, v118
	v_fmac_f32_e32 v4, v119, v119
	s_nop 1
	v_mov_b32_dpp v5, v4 row_ror:8 row_mask:0xf bank_mask:0xf
	v_add_f32_e32 v4, v4, v5
	s_nop 1
	v_mov_b32_dpp v5, v4 row_ror:4 row_mask:0xf bank_mask:0xf
	v_add_f32_e32 v4, v4, v5
	s_nop 1
	v_mov_b32_dpp v5, v4 row_ror:2 row_mask:0xf bank_mask:0xf
	v_add_f32_e32 v4, v4, v5
	s_nop 1
	v_mov_b32_dpp v5, v4 row_ror:1 row_mask:0xf bank_mask:0xf
	v_add_f32_e32 v4, v4, v5
	v_fma_f32 v4, v4, v37, v38
	v_rsq_f32_e32 v4, v4
	s_nop 0
	v_mul_f32_e32 v4, 0x3f4ccccd, v4
	v_mul_f32_e32 v112, v112, v4
	v_mul_f32_e32 v113, v113, v4
	v_mul_f32_e32 v114, v114, v4
	v_mul_f32_e32 v115, v115, v4
	v_mul_f32_e32 v116, v116, v4
	v_mul_f32_e32 v117, v117, v4
	v_mul_f32_e32 v118, v118, v4
	v_mul_f32_e32 v119, v119, v4
	v_cvt_pk_bf16_f32 v188, v112, v113
	v_cvt_pk_bf16_f32 v189, v114, v115
	v_cvt_pk_bf16_f32 v190, v116, v117
	v_cvt_pk_bf16_f32 v191, v118, v119
	v_add_u32_e32 v253, 0x2000, v253
	global_store_dwordx4 v253, v[188:191], s[86:87]
	v_lshlrev_b32_e32 v112, 16, v192
	v_and_b32_e32 v113, 0xffff0000, v192
	v_lshlrev_b32_e32 v114, 16, v193
	v_and_b32_e32 v115, 0xffff0000, v193
	v_lshlrev_b32_e32 v116, 16, v194
	v_and_b32_e32 v117, 0xffff0000, v194
	v_lshlrev_b32_e32 v118, 16, v195
	v_and_b32_e32 v119, 0xffff0000, v195
	v_mul_f32_e32 v4, v112, v112
	v_fmac_f32_e32 v4, v113, v113
	v_fmac_f32_e32 v4, v114, v114
	v_fmac_f32_e32 v4, v115, v115
	v_fmac_f32_e32 v4, v116, v116
	v_fmac_f32_e32 v4, v117, v117
	v_fmac_f32_e32 v4, v118, v118
	v_fmac_f32_e32 v4, v119, v119
	s_nop 1
	v_mov_b32_dpp v5, v4 row_ror:8 row_mask:0xf bank_mask:0xf
	v_add_f32_e32 v4, v4, v5
	s_nop 1
	v_mov_b32_dpp v5, v4 row_ror:4 row_mask:0xf bank_mask:0xf
	v_add_f32_e32 v4, v4, v5
	s_nop 1
	v_mov_b32_dpp v5, v4 row_ror:2 row_mask:0xf bank_mask:0xf
	v_add_f32_e32 v4, v4, v5
	s_nop 1
	v_mov_b32_dpp v5, v4 row_ror:1 row_mask:0xf bank_mask:0xf
	v_add_f32_e32 v4, v4, v5
	v_fma_f32 v4, v4, v37, v38
	v_rsq_f32_e32 v4, v4
	s_nop 0
	v_mul_f32_e32 v4, 0x3f4ccccd, v4
	v_mul_f32_e32 v112, v112, v4
	v_mul_f32_e32 v113, v113, v4
	v_mul_f32_e32 v114, v114, v4
	v_mul_f32_e32 v115, v115, v4
	v_mul_f32_e32 v116, v116, v4
	v_mul_f32_e32 v117, v117, v4
	v_mul_f32_e32 v118, v118, v4
	v_mul_f32_e32 v119, v119, v4
	v_cvt_pk_bf16_f32 v192, v112, v113
	v_cvt_pk_bf16_f32 v193, v114, v115
	v_cvt_pk_bf16_f32 v194, v116, v117
	v_cvt_pk_bf16_f32 v195, v118, v119
; __device__ __forceinline__ unsigned cvtpk_s(float lo,float hi){f32x2_t v={lo,hi};bf16x2_t b=__builtin_convertvector(v,bf16x2_t);return __builtin_bit_cast(unsigned,b);}
; #define ATTN_STORE16(p,v) st16_wt((p),(v))
;     ...
;     } else if(emode==3){
;       #pragma unroll
;       for(int i=0;i<4;++i){const int row=i*8+(lane>>3),ch=lane&7;
;         const u32x4 v0=*(const u32x4*)(stg+row*64+ch*8), v1=*(const u32x4*)(stg+2048+row*64+ch*8);
;         float f[16]; float ss=0.f;
;         #pragma unroll
;         for(int j=0;j<4;++j){ f[2*j]=__uint_as_float(v0[j]<<16); f[2*j+1]=__uint_as_float(v0[j]&0xffff0000u); f[8+2*j]=__uint_as_float(v1[j]<<16); f[8+2*j+1]=__uint_as_float(v1[j]&0xffff0000u); }
;         #pragma unroll
;         for(int j=0;j<16;++j)ss+=f[j]*f[j];
;         ss+=__shfl_xor(ss,1); ss+=__shfl_xor(ss,2); ss+=__shfl_xor(ss,4);
;         const float rn=__builtin_amdgcn_rsqf(ss*(1.f/128.f)+1e-6f)*0.8f;
;         u32x4 w0,w1;
;         #pragma unroll
;         for(int j=0;j<4;++j){ w0[j]=cvtpk_s(f[2*j]*rn,f[2*j+1]*rn); w1[j]=cvtpk_s(f[8+2*j]*rn,f[8+2*j+1]*rn); }
;         ATTN_STORE16(Ow+(long)row*OP+ch*8,w0); ATTN_STORE16(Ow+(long)row*OP+64+ch*8,w1);}
;     }
;   }
;   asm volatile("s_waitcnt lgkmcnt(0)\n\ts_barrier":::"memory");
	v_add_u32_e32 v253, 0x2000, v253
	global_store_dwordx4 v253, v[192:195], s[86:87]
	v_lshlrev_b32_e32 v112, 16, v196
	v_and_b32_e32 v113, 0xffff0000, v196
	v_lshlrev_b32_e32 v114, 16, v197
	v_and_b32_e32 v115, 0xffff0000, v197
	v_lshlrev_b32_e32 v116, 16, v198
	v_and_b32_e32 v117, 0xffff0000, v198
	v_lshlrev_b32_e32 v118, 16, v199
	v_and_b32_e32 v119, 0xffff0000, v199
	v_mul_f32_e32 v4, v112, v112
	v_fmac_f32_e32 v4, v113, v113
	v_fmac_f32_e32 v4, v114, v114
	v_fmac_f32_e32 v4, v115, v115
	v_fmac_f32_e32 v4, v116, v116
	v_fmac_f32_e32 v4, v117, v117
	v_fmac_f32_e32 v4, v118, v118
	v_fmac_f32_e32 v4, v119, v119
	s_nop 1
	v_mov_b32_dpp v5, v4 row_ror:8 row_mask:0xf bank_mask:0xf
	v_add_f32_e32 v4, v4, v5
	s_nop 1
	v_mov_b32_dpp v5, v4 row_ror:4 row_mask:0xf bank_mask:0xf
	v_add_f32_e32 v4, v4, v5
	s_nop 1
	v_mov_b32_dpp v5, v4 row_ror:2 row_mask:0xf bank_mask:0xf
	v_add_f32_e32 v4, v4, v5
	s_nop 1
	v_mov_b32_dpp v5, v4 row_ror:1 row_mask:0xf bank_mask:0xf
	v_add_f32_e32 v4, v4, v5
	v_fma_f32 v4, v4, v37, v38
	v_rsq_f32_e32 v4, v4
	s_nop 0
	v_mul_f32_e32 v4, 0x3f4ccccd, v4
	v_mul_f32_e32 v112, v112, v4
	v_mul_f32_e32 v113, v113, v4
	v_mul_f32_e32 v114, v114, v4
	v_mul_f32_e32 v115, v115, v4
	v_mul_f32_e32 v116, v116, v4
	v_mul_f32_e32 v117, v117, v4
	v_mul_f32_e32 v118, v118, v4
	v_mul_f32_e32 v119, v119, v4
	v_cvt_pk_bf16_f32 v196, v112, v113
	v_cvt_pk_bf16_f32 v197, v114, v115
	v_cvt_pk_bf16_f32 v198, v116, v117
	v_cvt_pk_bf16_f32 v199, v118, v119
	v_add_u32_e32 v253, 0x2000, v253
	global_store_dwordx4 v253, v[196:199], s[86:87]
	v_lshlrev_b32_e32 v112, 16, v200
	v_and_b32_e32 v113, 0xffff0000, v200
	v_lshlrev_b32_e32 v114, 16, v201
	v_and_b32_e32 v115, 0xffff0000, v201
	v_lshlrev_b32_e32 v116, 16, v202
	v_and_b32_e32 v117, 0xffff0000, v202
	v_lshlrev_b32_e32 v118, 16, v203
	v_and_b32_e32 v119, 0xffff0000, v203
	v_mul_f32_e32 v4, v112, v112
	v_fmac_f32_e32 v4, v113, v113
	v_fmac_f32_e32 v4, v114, v114
	v_fmac_f32_e32 v4, v115, v115
	v_fmac_f32_e32 v4, v116, v116
	v_fmac_f32_e32 v4, v117, v117
	v_fmac_f32_e32 v4, v118, v118
	v_fmac_f32_e32 v4, v119, v119
	s_nop 1
	v_mov_b32_dpp v5, v4 row_ror:8 row_mask:0xf bank_mask:0xf
	v_add_f32_e32 v4, v4, v5
	s_nop 1
	v_mov_b32_dpp v5, v4 row_ror:4 row_mask:0xf bank_mask:0xf
	v_add_f32_e32 v4, v4, v5
	s_nop 1
	v_mov_b32_dpp v5, v4 row_ror:2 row_mask:0xf bank_mask:0xf
	v_add_f32_e32 v4, v4, v5
	s_nop 1
	v_mov_b32_dpp v5, v4 row_ror:1 row_mask:0xf bank_mask:0xf
	v_add_f32_e32 v4, v4, v5
	v_fma_f32 v4, v4, v37, v38
	v_rsq_f32_e32 v4, v4
	s_nop 0
	v_mul_f32_e32 v4, 0x3f4ccccd, v4
	v_mul_f32_e32 v112, v112, v4
	v_mul_f32_e32 v113, v113, v4
	v_mul_f32_e32 v114, v114, v4
	v_mul_f32_e32 v115, v115, v4
	v_mul_f32_e32 v116, v116, v4
	v_mul_f32_e32 v117, v117, v4
	v_mul_f32_e32 v118, v118, v4
	v_mul_f32_e32 v119, v119, v4
	v_cvt_pk_bf16_f32 v200, v112, v113
	v_cvt_pk_bf16_f32 v201, v114, v115
	v_cvt_pk_bf16_f32 v202, v116, v117
	v_cvt_pk_bf16_f32 v203, v118, v119
	v_add_u32_e32 v253, 0x2000, v253
	global_store_dwordx4 v253, v[200:203], s[86:87]
	v_lshlrev_b32_e32 v112, 16, v204
	v_and_b32_e32 v113, 0xffff0000, v204
	v_lshlrev_b32_e32 v114, 16, v205
	v_and_b32_e32 v115, 0xffff0000, v205
	v_lshlrev_b32_e32 v116, 16, v206
	v_and_b32_e32 v117, 0xffff0000, v206
	v_lshlrev_b32_e32 v118, 16, v207
	v_and_b32_e32 v119, 0xffff0000, v207
	v_mul_f32_e32 v4, v112, v112
	v_fmac_f32_e32 v4, v113, v113
	v_fmac_f32_e32 v4, v114, v114
	v_fmac_f32_e32 v4, v115, v115
	v_fmac_f32_e32 v4, v116, v116
	v_fmac_f32_e32 v4, v117, v117
	v_fmac_f32_e32 v4, v118, v118
	v_fmac_f32_e32 v4, v119, v119
	s_nop 1
	v_mov_b32_dpp v5, v4 row_ror:8 row_mask:0xf bank_mask:0xf
	v_add_f32_e32 v4, v4, v5
	s_nop 1
	v_mov_b32_dpp v5, v4 row_ror:4 row_mask:0xf bank_mask:0xf
	v_add_f32_e32 v4, v4, v5
	s_nop 1
	v_mov_b32_dpp v5, v4 row_ror:2 row_mask:0xf bank_mask:0xf
	v_add_f32_e32 v4, v4, v5
	s_nop 1
	v_mov_b32_dpp v5, v4 row_ror:1 row_mask:0xf bank_mask:0xf
	v_add_f32_e32 v4, v4, v5
	v_fma_f32 v4, v4, v37, v38
	v_rsq_f32_e32 v4, v4
	s_nop 0
	v_mul_f32_e32 v4, 0x3f4ccccd, v4
	v_mul_f32_e32 v112, v112, v4
	v_mul_f32_e32 v113, v113, v4
	v_mul_f32_e32 v114, v114, v4
	v_mul_f32_e32 v115, v115, v4
	v_mul_f32_e32 v116, v116, v4
	v_mul_f32_e32 v117, v117, v4
	v_mul_f32_e32 v118, v118, v4
	v_mul_f32_e32 v119, v119, v4
	v_cvt_pk_bf16_f32 v204, v112, v113
	v_cvt_pk_bf16_f32 v205, v114, v115
	v_cvt_pk_bf16_f32 v206, v116, v117
	v_cvt_pk_bf16_f32 v207, v118, v119
	v_add_u32_e32 v253, 0x2000, v253
	global_store_dwordx4 v253, v[204:207], s[86:87]
	s_waitcnt vmcnt(0) lgkmcnt(0)
	s_barrier
	s_nop 0
	s_branch .LBB0_1511
